# second V-half attention units: the causal-band steps (not the final step) also skip the row-max chain and rescale test, the reference from the sibling unit already bounds them
# baseline (speedup 1.0000x reference)
.LBB0_402:
	s_bitcmp1_b32 s46, 0
	s_cbranch_scc0 .Lj0_b1
	s_mov_b64 s[8:9], 0
	s_branch .LBB0_403

.LBB0_417:
	s_bitcmp1_b32 s46, 0
	s_cbranch_scc0 .Lj0_b2
	s_mov_b64 s[90:91], 0
	s_branch .LBB0_418
